# scan phase: the 32 log-forget loads per thread issued together with one wait (hipcc had 16 serial load-pair round trips), same additions in the same order
# speedup vs baseline: 1.0041x; 1.0041x over previous
; #define LAS __attribute__((address_space(3)))
; DI int opaque_tid() { int t = threadIdx.x; asm volatile("" : "+v"(t)); return t; }
; DI void scan_phase(const Args& a, LAS unsigned char* lds) {
;     ...
;     const int seq = blockIdx.x, b = seq >> 3, h = seq & 7, tid = opaque_tid(), lane = tid & 63, wave = tid >> 6;
;     const float* LF = (const float*)(a.ws + WS_LF); float* CK = (float*)(a.ws + WS_CK) + (size_t)seq * SEQ; u32x4* KX = (u32x4*)(a.ws + WS_KX) + (size_t)seq * SEQ;
;     LAS float* wt = (LAS float*)lds;
;     float v[32]; float run = 0.f;
; #pragma unroll
;     for (int j = 0; j < 32; ++j) { run += LF[((size_t)b * SEQ + tid * 32 + j) * 8 + h]; v[j] = run; }
;     float inc = run;
; #pragma unroll
;     for (int o = 1; o < 64; o <<= 1) { const float t = __shfl_up(inc, o); if (lane >= o) inc += t; }
;     if (lane == 63) wt[wave] = inc;
;     __syncthreads();
;     float base = inc - run;
;     for (int w = 0; w < wave; ++w) base += wt[w];
.LBB0_520:
	v_readlane_b32 s0, v252, 43
	v_readlane_b32 s1, v252, 44
	s_andn2_b64 vcc, exec, s[0:1]
	s_cbranch_vccnz .LBB0_534
	v_mov_b32_e32 v1, v236
	v_readlane_b32 s0, v254, 11
	v_lshlrev_b32_e32 v32, 5, v1
	v_ashrrev_i32_e32 v33, 31, v32
	v_readlane_b32 s1, v254, 12
	v_and_b32_e32 v38, 64, v240
	v_and_b32_e32 v3, 63, v1
	s_waitcnt lgkmcnt(0)
	v_lshl_add_u64 v[4:5], v[32:33], 0, s[0:1]
	v_readlane_b32 s0, v252, 45
	v_lshlrev_b64 v[4:5], 5, v[4:5]
	v_readlane_b32 s1, v252, 46
	v_add_u32_e32 v39, -2, v240
	s_nop 0
	v_lshl_add_u64 v[4:5], s[0:1], 0, v[4:5]
	global_load_dword v100, v[4:5], off
	global_load_dword v101, v[4:5], off offset:32
	global_load_dword v102, v[4:5], off offset:64
	global_load_dword v103, v[4:5], off offset:96
	global_load_dword v104, v[4:5], off offset:128
	global_load_dword v105, v[4:5], off offset:160
	global_load_dword v106, v[4:5], off offset:192
	global_load_dword v107, v[4:5], off offset:224
	global_load_dword v108, v[4:5], off offset:256
	global_load_dword v109, v[4:5], off offset:288
	global_load_dword v110, v[4:5], off offset:320
	global_load_dword v111, v[4:5], off offset:352
	global_load_dword v112, v[4:5], off offset:384
	global_load_dword v113, v[4:5], off offset:416
	global_load_dword v114, v[4:5], off offset:448
	global_load_dword v115, v[4:5], off offset:480
	global_load_dword v116, v[4:5], off offset:512
	global_load_dword v117, v[4:5], off offset:544
	global_load_dword v118, v[4:5], off offset:576
	global_load_dword v119, v[4:5], off offset:608
	global_load_dword v120, v[4:5], off offset:640
	global_load_dword v121, v[4:5], off offset:672
	global_load_dword v122, v[4:5], off offset:704
	global_load_dword v123, v[4:5], off offset:736
	global_load_dword v124, v[4:5], off offset:768
	global_load_dword v125, v[4:5], off offset:800
	global_load_dword v126, v[4:5], off offset:832
	global_load_dword v127, v[4:5], off offset:864
	global_load_dword v128, v[4:5], off offset:896
	global_load_dword v129, v[4:5], off offset:928
	global_load_dword v130, v[4:5], off offset:960
	global_load_dword v131, v[4:5], off offset:992
	s_waitcnt vmcnt(0)
	v_add_f32_e32 v0, 0, v100
	v_add_f32_e32 v36, v0, v101
	v_add_f32_e32 v37, v36, v102
	v_add_f32_e32 v30, v37, v103
	v_add_f32_e32 v31, v30, v104
	v_add_f32_e32 v28, v31, v105
	v_add_f32_e32 v29, v28, v106
	v_add_f32_e32 v26, v29, v107
	v_add_f32_e32 v27, v26, v108
	v_add_f32_e32 v24, v27, v109
	v_add_f32_e32 v25, v24, v110
	v_add_f32_e32 v22, v25, v111
	v_add_f32_e32 v23, v22, v112
	v_add_f32_e32 v20, v23, v113
	v_add_f32_e32 v21, v20, v114
	v_add_f32_e32 v18, v21, v115
	v_add_f32_e32 v19, v18, v116
	v_add_f32_e32 v16, v19, v117
	v_add_f32_e32 v17, v16, v118
	v_add_f32_e32 v14, v17, v119
	v_add_f32_e32 v15, v14, v120
	v_add_f32_e32 v35, v15, v121
	v_add_f32_e32 v12, v35, v122
	v_add_f32_e32 v13, v12, v123
	v_add_f32_e32 v10, v13, v124
	v_add_f32_e32 v11, v10, v125
	v_add_f32_e32 v8, v11, v126
	v_add_f32_e32 v9, v8, v127
	v_add_f32_e32 v6, v9, v128
	v_add_f32_e32 v7, v6, v129
	v_add_f32_e32 v4, v7, v130
	v_add_u32_e32 v34, -1, v240
	v_cmp_lt_i32_e32 vcc, v34, v38
	s_nop 0
	v_add_f32_e32 v5, v4, v131
	v_cndmask_b32_e32 v34, v34, v240, vcc
	v_lshlrev_b32_e32 v34, 2, v34
	ds_bpermute_b32 v34, v34, v5
	v_cmp_eq_u32_e32 vcc, 0, v3
	s_waitcnt lgkmcnt(0)
	v_add_f32_e32 v34, v5, v34
	v_cndmask_b32_e32 v34, v34, v5, vcc
	v_cmp_lt_i32_e32 vcc, v39, v38
	s_nop 1
	v_cndmask_b32_e32 v39, v39, v240, vcc
	v_lshlrev_b32_e32 v39, 2, v39
	ds_bpermute_b32 v39, v39, v34
	v_cmp_gt_u32_e32 vcc, 2, v3
	s_waitcnt lgkmcnt(0)
	v_add_f32_e32 v39, v34, v39
	v_cndmask_b32_e32 v34, v39, v34, vcc
	v_add_u32_e32 v39, -4, v240
	v_cmp_lt_i32_e32 vcc, v39, v38
	s_nop 1
	v_cndmask_b32_e32 v39, v39, v240, vcc
	v_lshlrev_b32_e32 v39, 2, v39
	ds_bpermute_b32 v39, v39, v34
	v_cmp_gt_u32_e32 vcc, 4, v3
	s_waitcnt lgkmcnt(0)
	v_add_f32_e32 v39, v34, v39
	v_cndmask_b32_e32 v34, v39, v34, vcc
	v_add_u32_e32 v39, -8, v240
	v_cmp_lt_i32_e32 vcc, v39, v38
	s_nop 1
	v_cndmask_b32_e32 v39, v39, v240, vcc
	v_lshlrev_b32_e32 v39, 2, v39
	ds_bpermute_b32 v39, v39, v34
	v_cmp_gt_u32_e32 vcc, 8, v3
	s_waitcnt lgkmcnt(0)
	v_add_f32_e32 v39, v34, v39
	v_cndmask_b32_e32 v34, v39, v34, vcc
	v_add_u32_e32 v39, -16, v240
	v_cmp_lt_i32_e32 vcc, v39, v38
	s_nop 1
	v_cndmask_b32_e32 v39, v39, v240, vcc
	v_lshlrev_b32_e32 v39, 2, v39
	ds_bpermute_b32 v39, v39, v34
	v_cmp_gt_u32_e32 vcc, 16, v3
	s_waitcnt lgkmcnt(0)
	v_add_f32_e32 v39, v34, v39
	v_cndmask_b32_e32 v34, v39, v34, vcc
	v_subrev_u32_e32 v39, 32, v240
	v_cmp_lt_i32_e32 vcc, v39, v38
	s_nop 1
	v_cndmask_b32_e32 v38, v39, v240, vcc
	v_lshlrev_b32_e32 v38, 2, v38
	ds_bpermute_b32 v38, v38, v34
	v_cmp_eq_u32_e32 vcc, 63, v3
	s_waitcnt lgkmcnt(0)
	v_add_f32_e32 v39, v34, v38
	v_ashrrev_i32_e32 v38, 6, v1
	s_and_saveexec_b64 s[0:1], vcc
	v_lshl_add_u32 v40, v38, 2, 0
	ds_write_b32 v40, v39
	s_or_b64 exec, exec, s[0:1]
	v_cmp_gt_u32_e32 vcc, 32, v3
	s_waitcnt lgkmcnt(0)
	s_barrier
	v_cndmask_b32_e32 v3, v39, v34, vcc
	v_sub_f32_e32 v34, v3, v5
	v_cmp_lt_i32_e32 vcc, 0, v38
	s_and_saveexec_b64 s[0:1], vcc
	s_cbranch_execz .LBB0_533
	v_cmp_lt_u32_e32 vcc, 7, v38
	v_mov_b32_e32 v3, 0
	s_and_saveexec_b64 s[2:3], vcc
	s_cbranch_execz .LBB0_528
	v_and_b32_e32 v3, 0x7ffffff8, v38
	s_mov_b32 s6, 0
	s_mov_b32 s7, 0
	s_mov_b64 s[4:5], 0
